# GEMM prologues: K-tile 1 staging loads issued before the K-tile 0 wait (two cold round trips overlap)
# baseline (speedup 1.0000x reference)
.LBB0_65:
	v_writelane_b32 v255, s58, 17
	s_and_b64 s[30:31], s[58:59], exec
	s_cselect_b32 s27, 0, 0xffffffe0
	s_lshl_b32 s25, s25, 5
	s_and_b32 s25, s25, 0x60
	s_add_i32 m0, s51, 0x18000
	v_lshl_add_u64 v[6:7], v[6:7], 0, s[88:89]
	s_lshl_b32 s40, s24, 13
	s_lshl_b32 s41, s25, 7
	global_load_lds_dwordx4 v[6:7], off
	v_lshl_add_u64 v[4:5], v[4:5], 0, s[88:89]
	s_add_i32 m0, s51, 0x1a000
	s_add_i32 s78, s51, 0x8000
	s_add_i32 s79, s51, 0xa000
	global_load_lds_dwordx4 v[4:5], off
	v_lshl_add_u64 v[0:1], v[0:1], 0, s[88:89]
	s_mov_b32 m0, s78
	s_add_u32 s30, s66, 0x40080
	global_load_lds_dwordx4 v[0:1], off
	v_lshl_add_u64 v[0:1], v[2:3], 0, s[88:89]
	s_mov_b32 m0, s79
	s_addc_u32 s31, s67, 0
	global_load_lds_dwordx4 v[0:1], off
	s_add_i32 m0, s51, 0x1c000
	v_lshl_add_u64 v[0:1], s[30:31], 0, v[32:33]
	global_load_lds_dwordx4 v[0:1], off
	v_lshl_add_u64 v[0:1], s[30:31], 0, v[136:137]
	s_add_i32 m0, s51, 0x1e000
	s_cmpk_lt_u32 s0, 0x100
	global_load_lds_dwordx4 v[0:1], off
	s_waitcnt vmcnt(8)
	s_barrier
	v_lshrrev_b32_e32 v1, 1, v8
	v_and_b32_e32 v1, 24, v1
	v_and_b32_e32 v0, 15, v8
	v_lshlrev_b32_e32 v2, 1, v1
	v_lshl_or_b32 v37, s24, 6, v0
	v_lshl_or_b32 v0, v0, 6, v2
	v_lshlrev_b32_e32 v2, 2, v8
	v_and_b32_e32 v2, 32, v2
	v_bitop3_b32 v3, v0, s40, v2 bitop3:0xde
	v_bitop3_b32 v146, v0, s41, v2 bitop3:0xde
	v_lshlrev_b32_e32 v0, 14, v9
	v_and_b32_e32 v0, 0xffff8000, v0
	s_cselect_b64 s[54:55], -1, 0
	s_waitcnt lgkmcnt(0)
	s_add_i32 s43, s71, s27
	v_readlane_b32 s27, v252, 0
	v_or_b32_e32 v147, s25, v1
	v_lshl_add_u32 v0, v10, 11, v0
	v_and_b32_e32 v1, 1, v9
	s_cmp_lt_i32 s27, s43
	v_lshl_or_b32 v0, v1, 6, v0
	v_writelane_b32 v255, s59, 18
	s_cselect_b64 s[56:57], -1, 0
	s_ashr_i32 s40, s71, 31
	s_mul_i32 s24, s71, 3
	s_ashr_i32 s30, s43, 31
	v_lshl_add_u32 v138, v11, 1, v0
	v_lshlrev_b32_e32 v0, 14, v12
	v_writelane_b32 v255, s30, 19
	s_add_u32 s24, s24, s27
	v_and_b32_e32 v0, 0xffff8000, v0
	s_waitcnt vmcnt(6)
	s_mul_hi_i32 s0, s71, 3
	v_writelane_b32 v255, s24, 21
	v_readlane_b32 s24, v252, 22
	v_lshl_add_u32 v0, v13, 11, v0
	v_and_b32_e32 v1, 1, v12
	s_addc_u32 s0, s0, s24
	v_lshl_or_b32 v0, v1, 6, v0
	s_mov_b32 s42, 0
	v_writelane_b32 v255, s0, 23
	s_mov_b32 s49, s1
	s_mov_b32 s47, s1
	v_mov_b32_e32 v139, v33
	v_lshl_add_u32 v140, v14, 1, v0
	v_mov_b32_e32 v141, v33
	v_add_u32_e32 v148, 0, v3
	s_barrier
	s_branch .LBB0_68

.LBB0_178:
	s_and_b32 s46, s0, 3
	s_add_i32 m0, s63, 0x18000
	v_lshl_add_u64 v[4:5], v[4:5], 0, s[88:89]
	s_lshl_b32 s44, s30, 6
	s_lshl_b32 s42, s30, 13
	s_lshl_b32 s43, s46, 12
	global_load_lds_dwordx4 v[4:5], off
	v_lshl_add_u64 v[2:3], v[2:3], 0, s[88:89]
	s_add_i32 m0, s63, 0x1a000
	s_add_i32 s76, s63, 0x8000
	s_add_i32 s77, s63, 0xa000
	global_load_lds_dwordx4 v[2:3], off
	v_lshl_add_u64 v[0:1], v[0:1], 0, s[88:89]
	s_mov_b32 m0, s76
	s_add_u32 s30, s34, 0x40080
	global_load_lds_dwordx4 v[0:1], off
	v_lshl_add_u64 v[0:1], v[6:7], 0, s[88:89]
	s_mov_b32 m0, s77
	s_addc_u32 s31, s35, 0
	global_load_lds_dwordx4 v[0:1], off
	s_add_i32 m0, s63, 0x1c000
	v_lshl_add_u64 v[0:1], s[30:31], 0, v[136:137]
	global_load_lds_dwordx4 v[0:1], off
	v_lshl_add_u64 v[0:1], s[30:31], 0, v[34:35]
	s_add_i32 m0, s63, 0x1e000
	v_bfe_u32 v2, v10, 4, 2
	global_load_lds_dwordx4 v[0:1], off
	s_waitcnt vmcnt(8)
	s_barrier
	s_cmpk_lt_u32 s25, 0x100
	v_and_b32_e32 v1, 15, v10
	v_lshlrev_b32_e32 v4, 4, v2
	s_cselect_b64 s[52:53], -1, 0
	s_bfe_u32 s30, s0, 0x10001
	s_lshl_b32 s25, s0, 1
	s_lshl_b32 s0, s0, 2
	v_or_b32_e32 v37, s44, v1
	v_lshlrev_b32_e32 v3, 3, v2
	v_lshl_or_b32 v4, v1, 6, v4
	v_lshlrev_b32_e32 v5, 2, v1
	v_and_or_b32 v2, s0, 4, v2
	v_lshlrev_b32_e32 v1, 3, v1
	v_and_b32_e32 v6, 32, v5
	v_lshl_or_b32 v2, v2, 7, v1
	v_lshlrev_b32_e32 v1, 14, v13
	v_bitop3_b32 v7, v4, s42, v6 bitop3:0xde
	v_bitop3_b32 v148, v4, s43, v6 bitop3:0xde
	v_and_b32_e32 v6, 1, v10
	v_and_b32_e32 v1, 0xffff8000, v1
	v_lshrrev_b32_e32 v0, 4, v10
	s_mov_b32 s38, s44
	v_cmp_eq_u32_e64 s[44:45], 0, v6
	v_and_b32_e32 v6, 8, v3
	v_lshl_or_b32 v149, s46, 5, v3
	v_lshl_add_u32 v1, v12, 11, v1
	v_and_b32_e32 v3, 1, v13
	v_bfe_u32 v0, v0, 1, 1
	v_lshl_or_b32 v1, v3, 6, v1
	v_and_or_b32 v0, s25, 2, v0
	v_and_b32_e32 v5, 48, v5
	v_lshl_add_u32 v140, v14, 1, v1
	v_lshlrev_b32_e32 v1, 14, v8
	v_and_b32_e32 v4, 3, v10
	v_lshl_or_b32 v0, v0, 6, v5
	s_or_b32 s25, s30, 0xffffffe0
	v_and_b32_e32 v1, 0xffff8000, v1
	s_waitcnt vmcnt(6)
	v_or3_b32 v0, v0, v6, v4
	v_writelane_b32 v255, s25, 34
	v_lshl_add_u32 v1, v9, 11, v1
	v_and_b32_e32 v3, 1, v8
	v_lshlrev_b32_e32 v0, 3, v0
	v_writelane_b32 v255, s30, 15
	s_or_b32 s25, s30, 0xffffffe2
	v_lshl_or_b32 v1, v3, 6, v1
	v_cmp_gt_u32_e64 s[42:43], 2, v4
	s_mov_b32 s79, 0
	v_writelane_b32 v255, s25, 27
	s_waitcnt lgkmcnt(0)
	s_ashr_i32 s78, s40, 31
	s_mov_b32 s25, s1
	v_mov_b32_e32 v141, v33
	v_lshl_add_u32 v142, v11, 1, v1
	v_mov_b32_e32 v143, v33
	v_add_u32_e32 v150, 0, v7
	v_lshlrev_b32_e32 v151, 1, v0
	v_lshlrev_b32_e32 v32, 1, v2
	s_barrier
	s_branch .LBB0_181

.LBB0_452:
	v_lshl_add_u64 v[0:1], s[66:67], 0, v[32:33]
	v_mov_b32_e32 v135, v33
	v_lshl_add_u64 v[2:3], s[66:67], 0, v[134:135]
	s_add_i32 m0, s54, 0x18000
	v_lshl_add_u64 v[0:1], v[0:1], 0, s[88:89]
	v_lshl_add_u64 v[8:9], s[26:27], 0, v[32:33]
	global_load_lds_dwordx4 v[0:1], off
	v_lshl_add_u64 v[0:1], v[2:3], 0, s[88:89]
	s_add_i32 m0, s54, 0x1a000
	s_add_i32 s39, s54, 0x8000
	v_lshl_add_u64 v[10:11], s[26:27], 0, v[134:135]
	global_load_lds_dwordx4 v[0:1], off
	v_lshl_add_u64 v[0:1], v[8:9], 0, s[88:89]
	s_mov_b32 m0, s39
	s_add_i32 s97, s54, 0xa000
	v_lshl_add_u64 v[4:5], s[34:35], 0, v[32:33]
	global_load_lds_dwordx4 v[0:1], off
	v_lshl_add_u64 v[0:1], v[10:11], 0, s[88:89]
	s_mov_b32 m0, s97
	v_lshl_add_u64 v[6:7], s[34:35], 0, v[134:135]
	global_load_lds_dwordx4 v[0:1], off
	s_add_i32 m0, s54, 0x1c000
	v_lshl_add_u64 v[0:1], v[4:5], 0, s[88:89]
	global_load_lds_dwordx4 v[0:1], off
	v_lshl_add_u64 v[0:1], v[6:7], 0, s[88:89]
	s_add_i32 m0, s54, 0x1e000
	v_writelane_b32 v255, s2, 35
	global_load_lds_dwordx4 v[0:1], off
	s_waitcnt vmcnt(8)
	s_barrier
	v_and_b32_e32 v178, 15, v37
	v_readlane_b32 s0, v255, 34
	v_and_b32_e32 v0, 48, v37
	v_lshlrev_b32_e32 v1, 2, v37
	s_and_b32 s2, s2, 3
	v_lshl_or_b32 v34, s0, 6, v178
	s_lshl_b32 s0, s0, 13
	v_lshl_or_b32 v0, v178, 6, v0
	v_and_b32_e32 v1, 32, v1
	v_bitop3_b32 v4, v0, s0, v1 bitop3:0xde
	s_lshl_b32 s0, s2, 12
	v_bitop3_b32 v35, v0, s0, v1 bitop3:0xde
	s_and_b32 s0, s31, 3
	v_writelane_b32 v254, s0, 63
	s_lshr_b32 s0, s31, 2
	v_writelane_b32 v255, s2, 37
	s_add_i32 s0, s0, 64
	v_writelane_b32 v255, s0, 0
	s_ashr_i32 s0, s38, 31
	v_writelane_b32 v255, s0, 13
	s_and_b32 s28, s46, 4
	s_waitcnt vmcnt(6)
	s_lshr_b32 s0, s46, 3
	v_writelane_b32 v255, s28, 14
	v_mov_b32_e32 v2, v33
	v_mov_b32_e32 v3, v33
	v_writelane_b32 v255, s0, 8
	s_or_b32 s0, s0, 1
	v_mov_b32_e32 v0, v33
	v_mov_b32_e32 v1, v33
	v_add_u32_e32 v136, 0, v4
	v_mov_b64_e32 v[6:7], v[2:3]
	v_mov_b64_e32 v[14:15], v[2:3]
	v_mov_b64_e32 v[18:19], v[2:3]
	v_mov_b64_e32 v[30:31], v[2:3]
	v_mov_b64_e32 v[40:41], v[2:3]
	v_mov_b64_e32 v[52:53], v[2:3]
	v_mov_b64_e32 v[60:61], v[2:3]
	v_mov_b64_e32 v[10:11], v[2:3]
	v_mov_b64_e32 v[48:49], v[2:3]
	v_mov_b64_e32 v[22:23], v[2:3]
	v_mov_b64_e32 v[26:27], v[2:3]
	v_mov_b64_e32 v[44:45], v[2:3]
	v_mov_b64_e32 v[56:57], v[2:3]
	v_mov_b64_e32 v[64:65], v[2:3]
	v_mov_b64_e32 v[68:69], v[2:3]
	v_mov_b64_e32 v[72:73], v[2:3]
	v_mov_b64_e32 v[76:77], v[2:3]
	v_mov_b64_e32 v[84:85], v[2:3]
	v_mov_b64_e32 v[92:93], v[2:3]
	v_mov_b64_e32 v[104:105], v[2:3]
	v_mov_b64_e32 v[108:109], v[2:3]
	v_mov_b64_e32 v[116:117], v[2:3]
	v_mov_b64_e32 v[124:125], v[2:3]
	v_mov_b64_e32 v[80:81], v[2:3]
	v_mov_b64_e32 v[88:89], v[2:3]
	v_mov_b64_e32 v[96:97], v[2:3]
	v_mov_b64_e32 v[100:101], v[2:3]
	v_mov_b64_e32 v[112:113], v[2:3]
	v_mov_b64_e32 v[120:121], v[2:3]
	v_mov_b64_e32 v[128:129], v[2:3]
	v_mov_b64_e32 v[132:133], v[2:3]
	s_add_i32 s2, s30, -2
	s_mov_b32 s47, s1
	v_writelane_b32 v255, s0, 5
	s_mov_b32 s28, 0
	v_mov_b64_e32 v[4:5], v[0:1]
	v_mov_b64_e32 v[12:13], v[0:1]
	v_mov_b64_e32 v[16:17], v[0:1]
	v_mov_b64_e32 v[28:29], v[0:1]
	v_mov_b64_e32 v[38:39], v[0:1]
	v_mov_b64_e32 v[50:51], v[0:1]
	v_mov_b64_e32 v[58:59], v[0:1]
	v_mov_b64_e32 v[8:9], v[0:1]
	v_mov_b64_e32 v[46:47], v[0:1]
	v_mov_b64_e32 v[20:21], v[0:1]
	v_mov_b64_e32 v[24:25], v[0:1]
	v_mov_b64_e32 v[42:43], v[0:1]
	v_mov_b64_e32 v[54:55], v[0:1]
	v_mov_b64_e32 v[62:63], v[0:1]
	v_mov_b64_e32 v[66:67], v[0:1]
	v_mov_b64_e32 v[70:71], v[0:1]
	v_mov_b64_e32 v[74:75], v[0:1]
	v_mov_b64_e32 v[82:83], v[0:1]
	v_mov_b64_e32 v[90:91], v[0:1]
	v_mov_b64_e32 v[102:103], v[0:1]
	v_mov_b64_e32 v[106:107], v[0:1]
	v_mov_b64_e32 v[114:115], v[0:1]
	v_mov_b64_e32 v[122:123], v[0:1]
	v_mov_b64_e32 v[78:79], v[0:1]
	v_mov_b64_e32 v[86:87], v[0:1]
	v_mov_b64_e32 v[94:95], v[0:1]
	v_mov_b64_e32 v[98:99], v[0:1]
	v_mov_b64_e32 v[110:111], v[0:1]
	v_mov_b64_e32 v[118:119], v[0:1]
	v_mov_b64_e32 v[126:127], v[0:1]
	v_mov_b64_e32 v[130:131], v[0:1]
	s_barrier
	s_mov_b64 s[34:35], -1
	s_and_b64 vcc, exec, s[62:63]
	s_cbranch_vccz .LBB0_455

.LBB0_788:
	v_lshl_add_u64 v[6:7], s[26:27], 0, v[32:33]
	v_mov_b32_e32 v135, v33
	v_lshl_add_u64 v[8:9], s[26:27], 0, v[134:135]
	s_add_i32 m0, s51, 0x18000
	v_lshl_add_u64 v[6:7], v[6:7], 0, s[88:89]
	v_lshl_add_u64 v[14:15], s[24:25], 0, v[32:33]
	global_load_lds_dwordx4 v[6:7], off
	v_lshl_add_u64 v[6:7], v[8:9], 0, s[88:89]
	s_add_i32 m0, s51, 0x1a000
	s_add_i32 s64, s51, 0x8000
	v_lshl_add_u64 v[16:17], s[24:25], 0, v[134:135]
	global_load_lds_dwordx4 v[6:7], off
	v_lshl_add_u64 v[6:7], v[14:15], 0, s[88:89]
	s_mov_b32 m0, s64
	s_add_i32 s65, s51, 0xa000
	v_lshl_add_u64 v[10:11], s[34:35], 0, v[32:33]
	global_load_lds_dwordx4 v[6:7], off
	v_lshl_add_u64 v[6:7], v[16:17], 0, s[88:89]
	s_mov_b32 m0, s65
	v_lshl_add_u64 v[12:13], s[34:35], 0, v[134:135]
	global_load_lds_dwordx4 v[6:7], off
	s_add_i32 m0, s51, 0x1c000
	v_lshl_add_u64 v[6:7], v[10:11], 0, s[88:89]
	global_load_lds_dwordx4 v[6:7], off
	v_lshl_add_u64 v[6:7], v[12:13], 0, s[88:89]
	s_add_i32 m0, s51, 0x1e000
	v_and_b32_e32 v178, 15, v37
	global_load_lds_dwordx4 v[6:7], off
	s_waitcnt vmcnt(8)
	s_barrier
	v_and_b32_e32 v6, 48, v37
	v_lshlrev_b32_e32 v7, 2, v37
	s_and_b32 s45, s40, 3
	s_lshl_b32 s28, s41, 13
	v_lshl_or_b32 v6, v178, 6, v6
	v_and_b32_e32 v7, 32, v7
	v_bitop3_b32 v8, v6, s28, v7 bitop3:0xde
	s_lshl_b32 s28, s45, 12
	s_add_i32 s66, s30, -2
	s_add_u32 s34, s3, 0x80
	v_add_u32_e32 v0, v2, v0
	s_addc_u32 s35, 0, 0
	v_add_lshl_u32 v0, v0, v1, 1
	v_mov_b32_e32 v1, v33
	v_lshl_add_u64 v[136:137], s[34:35], 0, v[0:1]
	v_add_u32_e32 v0, v5, v3
	v_bitop3_b32 v35, v6, s28, v7 bitop3:0xde
	s_waitcnt vmcnt(6)
	v_add_lshl_u32 v0, v0, v4, 1
	v_mov_b32_e32 v2, v33
	v_mov_b32_e32 v3, v33
	v_readlane_b32 s28, v253, 19
	v_lshl_add_u64 v[138:139], s[34:35], 0, v[0:1]
	v_mov_b32_e32 v0, v33
	v_add_u32_e32 v144, 0, v8
	v_mov_b64_e32 v[6:7], v[2:3]
	v_mov_b64_e32 v[14:15], v[2:3]
	v_mov_b64_e32 v[18:19], v[2:3]
	v_mov_b64_e32 v[30:31], v[2:3]
	v_mov_b64_e32 v[40:41], v[2:3]
	v_mov_b64_e32 v[48:49], v[2:3]
	v_mov_b64_e32 v[56:57], v[2:3]
	v_mov_b64_e32 v[10:11], v[2:3]
	v_mov_b64_e32 v[60:61], v[2:3]
	v_mov_b64_e32 v[22:23], v[2:3]
	v_mov_b64_e32 v[26:27], v[2:3]
	v_mov_b64_e32 v[44:45], v[2:3]
	v_mov_b64_e32 v[52:53], v[2:3]
	v_mov_b64_e32 v[64:65], v[2:3]
	v_mov_b64_e32 v[68:69], v[2:3]
	v_mov_b64_e32 v[72:73], v[2:3]
	v_mov_b64_e32 v[76:77], v[2:3]
	v_mov_b64_e32 v[84:85], v[2:3]
	v_mov_b64_e32 v[92:93], v[2:3]
	v_mov_b64_e32 v[104:105], v[2:3]
	v_mov_b64_e32 v[108:109], v[2:3]
	v_mov_b64_e32 v[116:117], v[2:3]
	v_mov_b64_e32 v[124:125], v[2:3]
	v_mov_b64_e32 v[80:81], v[2:3]
	v_mov_b64_e32 v[88:89], v[2:3]
	v_mov_b64_e32 v[96:97], v[2:3]
	v_mov_b64_e32 v[100:101], v[2:3]
	v_mov_b64_e32 v[112:113], v[2:3]
	v_mov_b64_e32 v[120:121], v[2:3]
	v_mov_b64_e32 v[128:129], v[2:3]
	v_mov_b64_e32 v[132:133], v[2:3]
	s_mov_b32 s44, s28
	v_readlane_b32 s28, v253, 23
	v_lshl_or_b32 v34, s41, 6, v178
	s_mov_b32 s67, 0
	v_mov_b64_e32 v[4:5], v[0:1]
	v_mov_b64_e32 v[12:13], v[0:1]
	v_mov_b64_e32 v[16:17], v[0:1]
	v_mov_b64_e32 v[28:29], v[0:1]
	v_mov_b64_e32 v[38:39], v[0:1]
	v_mov_b64_e32 v[46:47], v[0:1]
	v_mov_b64_e32 v[54:55], v[0:1]
	v_mov_b64_e32 v[8:9], v[0:1]
	v_mov_b64_e32 v[58:59], v[0:1]
	v_mov_b64_e32 v[20:21], v[0:1]
	v_mov_b64_e32 v[24:25], v[0:1]
	v_mov_b64_e32 v[42:43], v[0:1]
	v_mov_b64_e32 v[50:51], v[0:1]
	v_mov_b64_e32 v[62:63], v[0:1]
	v_mov_b64_e32 v[66:67], v[0:1]
	v_mov_b64_e32 v[70:71], v[0:1]
	v_mov_b64_e32 v[74:75], v[0:1]
	v_mov_b64_e32 v[82:83], v[0:1]
	v_mov_b64_e32 v[90:91], v[0:1]
	v_mov_b64_e32 v[102:103], v[0:1]
	v_mov_b64_e32 v[106:107], v[0:1]
	v_mov_b64_e32 v[114:115], v[0:1]
	v_mov_b64_e32 v[122:123], v[0:1]
	v_mov_b64_e32 v[78:79], v[0:1]
	v_mov_b64_e32 v[86:87], v[0:1]
	v_mov_b64_e32 v[94:95], v[0:1]
	v_mov_b64_e32 v[98:99], v[0:1]
	v_mov_b64_e32 v[110:111], v[0:1]
	v_mov_b64_e32 v[118:119], v[0:1]
	v_mov_b64_e32 v[126:127], v[0:1]
	v_mov_b64_e32 v[130:131], v[0:1]
	s_mov_b32 s50, s28
	s_barrier
